# strategy: stagger - waves 4-7 sleep 64 cycles at each attention tile start to de-phase the two waves of a SIMD
# speedup vs baseline: 1.0039x; 1.0039x over previous
; __device__ __forceinline__ void attn_unit2f(unsigned char* ws, LAS unsigned char* lds, int s, int kvh, int qb, int hp, int tid, int wave, int lane) {
;     const int L = seq_L(s), Lp = seq_Lpad(s), ntile = Lp >> 7;
;     const int h0 = kvh * 4 + hp * 2;
;     const GAS bf16_t* Q = (const GAS bf16_t*)(ws + OFF_Q);
;     const GAS bf16_t* Kg = (const GAS bf16_t*)(ws + OFF_KP) + ((size_t)seq_koff(s) * 4 + (size_t)kvh * Lp) * 64;
;     const GAS bf16_t* Vg = (const GAS bf16_t*)(ws + OFF_VT) + (size_t)seq_koff(s) * 4 * 64 + (size_t)kvh * 64 * Lp;
;     GAS bf16_t* O = (GAS bf16_t*)(ws + OFF_B);
;     const int l31 = lane & 31, hi = lane >> 5, row = seq_base(s) + qb * 256 + wave * 32 + l31;
;     bf16x8 qf[2][4];
; #pragma unroll
;     for (int nh = 0; nh < 2; ++nh)
; #pragma unroll
;         for (int kk = 0; kk < 4; ++kk) qf[nh][kk] = *(const GAS bf16x8*)(Q + (size_t)row * 1024 + (h0 + nh) * 64 + 16 * kk + 8 * hi);
;     LAS bf16_t* Ks = (LAS bf16_t*)lds;
;     LAS bf16_t* Vs = (LAS bf16_t*)(lds + 2 * 128 * KPITCH * 2);
; __global__ void __launch_bounds__(512, 2) fwd_kernel(Params p) {
;     ...
;                     unsigned char* wsl = ws; asm volatile("" : "+s"(wsl)); wsl = (unsigned char*)(GAS unsigned char*)wsl;
;                     int tidl = tid; asm volatile("" : "+v"(tidl)); const int lanel = tidl & 63;
;                     if (tidl == 0) MISC[0] = (int)atomicAdd((unsigned*)(wsl + OFF_CTL) + 3, 1u);
;                     __syncthreads();
;                     const int u = __builtin_amdgcn_readfirstlane(MISC[0]);
;                     __syncthreads();
;                     if (u >= Q4) break;
;                     asm volatile("" : "+s"(fast_i));
;                     if (u < Q1) { if (fast_i) attn_unit2f(wsl, lds, 0, u >> 7, (u & 127) >> 1, u & 1, tidl, wave, lanel); else attn_unit2(wsl, lds, 0, u >> 7, (u & 127) >> 1, u & 1, tidl, wave, lanel, 0); }
;                     else if (u < Q3) { const int j = u - Q1, jj = j >> 1; const int cgl = jj < 128 ? 1 + jj : 129 + 17 * ((jj - 128) >> 4) + 1 + ((jj - 128) & 15);
;                         ssd_out_unit(p, lds, cgl * 2 + (j & 1), tidl, wave, lanel); }
;                     else { const int v = u - Q3; if (fast_i) attn_unit2f(wsl, lds, 1 + (v >> 6), (v >> 4) & 3, (v >> 1) & 7, v & 1, tidl, wave, lanel); else attn_unit2(wsl, lds, 1 + (v >> 6), (v >> 4) & 3, (v >> 1) & 7, v & 1, tidl, wave, lanel, 0); }
.LBB0_1157:
	s_or_b64 exec, exec, s[0:1]
	s_waitcnt lgkmcnt(0)
	s_barrier
	ds_read_b32 v0, v234
	s_waitcnt lgkmcnt(0)
	s_barrier
	v_readfirstlane_b32 s4, v0
	s_cmpk_gt_i32 s4, 0x5ff
	s_cselect_b64 s[0:1], -1, 0
	s_and_b64 vcc, exec, s[0:1]
	s_cbranch_vccnz .LBB0_1154
	v_writelane_b32 v255, s0, 5
	v_and_b32_e32 v236, 63, v235
	s_cmpk_gt_i32 s4, 0x1ff
	v_writelane_b32 v255, s1, 6
	v_readlane_b32 s0, v254, 29
	v_writelane_b32 v255, s4, 7
	s_nop 0
	v_writelane_b32 v254, s0, 29
	s_mov_b64 s[0:1], -1
	s_cbranch_scc0 .LBB0_1435
	v_readlane_b32 s0, v255, 7
	s_cmpk_gt_u32 s0, 0x3ff
	s_mov_b64 s[0:1], -1
	s_cbranch_scc0 .LBB0_1186
	v_readlane_b32 s32, v252, 48
	s_lshr_b32 s32, s32, 2
	v_readlane_b32 s6, v255, 7
	s_add_i32 s0, s6, 0xfffffc00
	s_bfe_u32 s4, s6, 0x20004
	s_lshl_b32 s9, s6, 7
	s_lshr_b32 s0, s0, 6
	s_lshl_b32 s5, s4, 8
	s_and_b32 s6, s9, 0x80
	s_lshl_b32 s1, s0, 11
	s_or_b32 s21, s5, s6
	s_add_u32 s6, s78, 0x205b1d00
	s_mul_i32 s0, s0, 0x110000
	s_addc_u32 s7, s79, 0
	s_add_i32 s76, s0, 0x810000
	s_mul_i32 s8, s4, 0x44000
	s_add_u32 s4, s78, 0x21641d00
	s_addc_u32 s5, s79, 0
	s_and_b32 s0, s9, 0x700
	s_or_b32 s0, s1, s0
	s_add_i32 s1, s0, 0x800
	s_lshl_b32 s0, s21, 1
	s_add_u32 s9, s6, s76
	s_addc_u32 s21, s7, 0
	s_add_u32 s24, s9, s8
	s_addc_u32 s25, s21, 0
	s_add_u32 s9, s4, s76
	s_addc_u32 s21, s5, 0
	s_add_u32 s26, s9, s8
	v_and_b32_e32 v240, 31, v235
	v_readlane_b32 s9, v254, 30
	v_lshrrev_b32_e32 v241, 5, v236
	v_lshlrev_b32_e32 v194, 4, v241
	v_or_b32_e32 v0, s9, v240
	v_add_u32_e32 v196, s1, v0
	v_ashrrev_i32_e32 v197, 31, v196
	v_lshlrev_b64 v[0:1], 11, v[196:197]
	v_lshl_add_u64 v[0:1], s[78:79], 0, v[0:1]
	v_lshl_add_u64 v[0:1], v[0:1], 0, v[194:195]
	s_mov_b32 s1, s77
	v_lshl_add_u64 v[0:1], v[0:1], 0, s[0:1]
	s_mov_b32 s1, 0x123f1000
	v_ashrrev_i32_e32 v6, 3, v235
	s_mov_b64 s[34:35], 0x123f1d00
	v_add_co_u32_e32 v4, vcc, s1, v0
	v_ashrrev_i32_e32 v7, 31, v6
	v_lshl_add_u64 v[2:3], v[0:1], 0, s[34:35]
	v_addc_co_u32_e32 v5, vcc, 0, v1, vcc
	v_lshlrev_b64 v[0:1], 7, v[6:7]
	v_lshlrev_b32_e32 v7, 4, v235
	v_lshl_add_u64 v[8:9], s[24:25], 0, v[0:1]
	v_and_b32_e32 v194, 0x70, v7
	global_load_dwordx4 v[128:131], v[2:3], off offset:64
	global_load_dwordx4 v[132:135], v[2:3], off offset:96
	v_lshl_add_u64 v[198:199], v[8:9], 0, v[194:195]
	global_load_dwordx4 v[136:139], v[2:3], off offset:32
	global_load_dwordx4 v[148:151], v[198:199], off
	s_addc_u32 s27, s21, 0
	v_mov_b64_e32 v[8:9], s[26:27]
	s_movk_i32 s1, 0x1100
	s_movk_i32 s9, 0x2000
	v_mad_i64_i32 v[8:9], s[24:25], v6, s1, v[8:9]
	v_add_co_u32_e32 v10, vcc, s9, v198
	v_lshl_add_u64 v[8:9], v[8:9], 0, v[194:195]
	s_nop 0
	v_addc_co_u32_e32 v11, vcc, 0, v199, vcc
	global_load_dwordx4 v[140:143], v[4:5], off offset:3328
	global_load_dwordx4 v[168:171], v[8:9], off
	global_load_dwordx4 v[164:167], v[10:11], off
	global_load_dwordx4 v[172:175], v[8:9], off offset:128
	global_load_dwordx4 v[144:147], v[2:3], off offset:128
	global_load_dwordx4 v[152:155], v[2:3], off offset:160
	global_load_dwordx4 v[156:159], v[2:3], off offset:192
	global_load_dwordx4 v[160:163], v[2:3], off offset:224
	v_mad_i64_i32 v[2:3], s[24:25], v6, s1, 0
	s_movk_i32 s1, 0x90
	s_mov_b32 s9, s77
	v_mul_lo_u32 v4, v6, s1
	v_mul_lo_u32 v5, v6, s30
	v_readlane_b32 s1, v254, 29
	v_lshlrev_b32_e32 v242, 3, v241
	v_lshlrev_b32_e32 v237, 2, v241
	v_lshlrev_b32_e32 v243, 7, v240
	v_add3_u32 v238, 0, v4, v194
	v_add3_u32 v239, 0, v5, v194
	s_cmp_eq_u32 s1, 0
	v_lshl_add_u64 v[200:201], s[8:9], 0, v[2:3]
	s_waitcnt vmcnt(8)
	ds_write_b128 v238, v[148:151]
	s_waitcnt vmcnt(5)
	ds_write_b128 v238, v[164:167] offset:9216
	ds_write_b128 v239, v[168:171] offset:36864
	s_waitcnt vmcnt(4)
	ds_write_b128 v239, v[172:175] offset:36992
	s_waitcnt lgkmcnt(0)
	s_cbranch_scc1 .LBB0_1164
	v_mad_u32_u24 v2, v240, s30, 0
	v_lshl_add_u32 v244, v241, 3, v2
	v_sub_u32_e32 v2, v2, v243
	v_lshl_add_u32 v245, v242, 1, v2
	v_and_b32_e32 v2, 7, v235
	v_lshl_add_u64 v[0:1], s[8:9], 0, v[0:1]
	v_lshlrev_b32_e32 v194, 4, v2
	v_lshl_add_u64 v[0:1], v[0:1], 0, v[194:195]
	v_lshl_add_u64 v[202:203], s[6:7], 0, v[0:1]
	v_lshl_add_u64 v[0:1], v[200:201], 0, v[194:195]
	v_lshl_add_u64 v[204:205], s[4:5], 0, v[0:1]
	v_mov_b32_e32 v0, 0
	s_mov_b32 s1, 0
	v_mov_b32_e32 v1, v0
	v_mov_b32_e32 v2, v0
	v_mov_b32_e32 v3, v0
	v_mov_b32_e32 v4, v0
	v_mov_b32_e32 v5, v0
	v_mov_b32_e32 v6, v0
	v_mov_b32_e32 v7, v0
	v_mov_b32_e32 v8, v0
	v_mov_b32_e32 v9, v0
	v_mov_b32_e32 v10, v0
	v_mov_b32_e32 v11, v0
	v_mov_b32_e32 v12, v0
	v_mov_b32_e32 v13, v0
	v_mov_b32_e32 v14, v0
	v_mov_b32_e32 v15, v0
	v_mov_b32_e32 v16, v0
	v_mov_b32_e32 v17, v0
	v_mov_b32_e32 v18, v0
	v_mov_b32_e32 v19, v0
	v_mov_b32_e32 v20, v0
	v_mov_b32_e32 v21, v0
	v_mov_b32_e32 v22, v0
	v_mov_b32_e32 v23, v0
	v_mov_b32_e32 v24, v0
	v_mov_b32_e32 v25, v0
	v_mov_b32_e32 v26, v0
	v_mov_b32_e32 v27, v0
	v_mov_b32_e32 v28, v0
	v_mov_b32_e32 v29, v0
	v_mov_b32_e32 v30, v0
	v_mov_b32_e32 v31, v0
	v_mov_b32_e32 v32, v0
	v_mov_b32_e32 v33, v0
	v_mov_b32_e32 v34, v0
	v_mov_b32_e32 v35, v0
	v_mov_b32_e32 v36, v0
	v_mov_b32_e32 v37, v0
	v_mov_b32_e32 v38, v0
	v_mov_b32_e32 v39, v0
	v_mov_b32_e32 v40, v0
	v_mov_b32_e32 v41, v0
	v_mov_b32_e32 v42, v0
	v_mov_b32_e32 v43, v0
	v_mov_b32_e32 v44, v0
	v_mov_b32_e32 v45, v0
	v_mov_b32_e32 v46, v0
	v_mov_b32_e32 v47, v0
	v_mov_b32_e32 v48, v0
	v_mov_b32_e32 v49, v0
	v_mov_b32_e32 v50, v0
	v_mov_b32_e32 v51, v0
	v_mov_b32_e32 v52, v0
	v_mov_b32_e32 v53, v0
	v_mov_b32_e32 v54, v0
	v_mov_b32_e32 v55, v0
	v_mov_b32_e32 v56, v0
	v_mov_b32_e32 v57, v0
	v_mov_b32_e32 v58, v0
	v_mov_b32_e32 v59, v0
	v_mov_b32_e32 v60, v0
	v_mov_b32_e32 v61, v0
	v_mov_b32_e32 v62, v0
	v_mov_b32_e32 v63, v0
	v_mov_b32_e32 v206, v0
	v_mov_b32_e32 v207, v0
	s_barrier
.LBB0_1162:
	s_cmp_eq_u32 s32, 0
	s_cbranch_scc1 .Ldp_skip1
	s_sleep 1

; #define LAS __attribute__((address_space(3)))
; #define GAS __attribute__((address_space(1)))
; __device__ __forceinline__ void attn_unit2f(unsigned char* ws, LAS unsigned char* lds, int s, int kvh, int qb, int hp, int tid, int wave, int lane) {
;     const int L = seq_L(s), Lp = seq_Lpad(s), ntile = Lp >> 7;
;     const int h0 = kvh * 4 + hp * 2;
;     const GAS bf16_t* Q = (const GAS bf16_t*)(ws + OFF_Q);
;     const GAS bf16_t* Kg = (const GAS bf16_t*)(ws + OFF_KP) + ((size_t)seq_koff(s) * 4 + (size_t)kvh * Lp) * 64;
;     const GAS bf16_t* Vg = (const GAS bf16_t*)(ws + OFF_VT) + (size_t)seq_koff(s) * 4 * 64 + (size_t)kvh * 64 * Lp;
;     GAS bf16_t* O = (GAS bf16_t*)(ws + OFF_B);
;     const int l31 = lane & 31, hi = lane >> 5, row = seq_base(s) + qb * 256 + wave * 32 + l31;
;     bf16x8 qf[2][4];
; #pragma unroll
;     for (int nh = 0; nh < 2; ++nh)
; #pragma unroll
;         for (int kk = 0; kk < 4; ++kk) qf[nh][kk] = *(const GAS bf16x8*)(Q + (size_t)row * 1024 + (h0 + nh) * 64 + 16 * kk + 8 * hi);
;     LAS bf16_t* Ks = (LAS bf16_t*)lds;
;     LAS bf16_t* Vs = (LAS bf16_t*)(lds + 2 * 128 * KPITCH * 2);
;     const int sr = tid >> 3, sc = (tid & 7) * 8;
;     const GAS bf16_t* kgp = Kg + (size_t)sr * 64 + sc;
;     const GAS bf16_t* vgp = Vg + (size_t)sr * Lp + sc;
;     u32x4 kreg0 = *(const GAS u32x4*)kgp, kreg1 = *(const GAS u32x4*)(kgp + 64 * 64), vreg0 = *(const GAS u32x4*)vgp, vreg1 = *(const GAS u32x4*)(vgp + 64);
;     *(LAS u32x4*)(Ks + sr * KPITCH + sc) = kreg0; *(LAS u32x4*)(Ks + (sr + 64) * KPITCH + sc) = kreg1;
;     *(LAS u32x4*)(Vs + sr * VPITCH + sc) = vreg0; *(LAS u32x4*)(Vs + sr * VPITCH + sc + 64) = vreg1;
;     __syncthreads();
;     f32x16 Oa0, Oa1, Ob0, Ob1;
; #pragma unroll
;     for (int i = 0; i < 16; ++i) { Oa0[i] = 0.f; Oa1[i] = 0.f; Ob0[i] = 0.f; Ob1[i] = 0.f; }
;     float lsa = 0.f, lsb = 0.f;
.LBB0_1435:
	s_andn2_b64 vcc, exec, s[0:1]
	s_cbranch_vccnz .LBB0_1153
	v_readlane_b32 s32, v252, 48
	s_lshr_b32 s32, s32, 2
	v_readlane_b32 s4, v255, 7
	s_ashr_i32 s1, s4, 7
	s_lshl_b32 s8, s4, 7
	s_lshl_b32 s0, s1, 8
	s_and_b32 s4, s8, 0x80
	s_or_b32 s0, s4, s0
	s_add_u32 s4, s78, 0x21641d00
	s_mul_hi_i32 s7, s1, 0x204000
	s_mul_i32 s6, s1, 0x204000
	s_addc_u32 s5, s79, 0
	s_and_b32 s1, s8, 0x3f00
	s_add_i32 s21, s1, s74
	v_and_b32_e32 v239, 31, v235
	v_or_b32_e32 v196, s21, v239
	v_ashrrev_i32_e32 v197, 31, v196
	v_lshrrev_b32_e32 v240, 5, v236
	v_lshlrev_b64 v[0:1], 11, v[196:197]
	v_lshl_add_u64 v[0:1], s[78:79], 0, v[0:1]
	v_lshlrev_b32_e32 v194, 4, v240
	s_ashr_i32 s1, s0, 31
	v_lshl_add_u64 v[0:1], v[0:1], 0, v[194:195]
	v_lshl_add_u64 v[0:1], s[0:1], 1, v[0:1]
	s_mov_b64 s[26:27], 0x123f1d00
	s_mov_b32 s21, 0x123f1000
	v_lshl_add_u64 v[2:3], v[0:1], 0, s[26:27]
	v_add_co_u32_e32 v0, vcc, s21, v0
	v_ashrrev_i32_e32 v200, 3, v235
	s_add_u32 s8, s78, s6
	v_addc_co_u32_e32 v1, vcc, 0, v1, vcc
	v_ashrrev_i32_e32 v201, 31, v200
	s_addc_u32 s9, s79, s7
	global_load_dwordx4 v[128:131], v[0:1], off offset:3328
	global_load_dwordx4 v[132:135], v[2:3], off offset:32
	global_load_dwordx4 v[136:139], v[2:3], off offset:64
	global_load_dwordx4 v[140:143], v[2:3], off offset:96
	global_load_dwordx4 v[144:147], v[2:3], off offset:128
	global_load_dwordx4 v[148:151], v[2:3], off offset:160
	global_load_dwordx4 v[152:155], v[2:3], off offset:192
	global_load_dwordx4 v[156:159], v[2:3], off offset:224
	v_lshlrev_b64 v[0:1], 7, v[200:201]
	s_add_u32 s24, s4, s6
	v_lshl_add_u64 v[0:1], s[8:9], 0, v[0:1]
	s_mov_b64 s[8:9], 0x205b1d00
	s_addc_u32 s25, s5, s7
	v_lshl_add_u64 v[202:203], v[0:1], 0, s[8:9]
	v_lshlrev_b32_e32 v0, 4, v235
	v_and_b32_e32 v194, 0x70, v0
	v_mov_b64_e32 v[0:1], s[24:25]
	s_mov_b32 s8, 0x8100
	v_mad_i64_i32 v[204:205], s[8:9], v200, s8, v[0:1]
	v_lshl_add_u64 v[198:199], v[202:203], 0, v[194:195]
	s_movk_i32 s8, 0x2000
	v_add_co_u32_e32 v2, vcc, s8, v198
	v_lshl_add_u64 v[0:1], v[204:205], 0, v[194:195]
	s_nop 0
	v_addc_co_u32_e32 v3, vcc, 0, v199, vcc
	global_load_dwordx4 v[160:163], v[198:199], off
	global_load_dwordx4 v[164:167], v[2:3], off
	global_load_dwordx4 v[168:171], v[0:1], off
	global_load_dwordx4 v[172:175], v[0:1], off offset:128
	s_movk_i32 s8, 0x90
	v_mul_lo_u32 v0, v200, s8
	v_add3_u32 v237, 0, v0, v194
	v_mul_lo_u32 v0, v200, s30
	v_readlane_b32 s23, v254, 29
	v_add3_u32 v238, 0, v0, v194
	v_and_b32_e32 v0, 7, v235
	s_cmp_eq_u32 s23, 0
	v_lshlrev_b32_e32 v241, 3, v240
	v_lshlrev_b32_e32 v236, 2, v240
	v_lshlrev_b32_e32 v201, 7, v239
	v_lshlrev_b32_e32 v194, 4, v0
	s_waitcnt vmcnt(3)
	ds_write_b128 v237, v[160:163]
	s_waitcnt vmcnt(2)
	ds_write_b128 v237, v[164:167] offset:9216
	s_waitcnt vmcnt(1)
	ds_write_b128 v238, v[168:171] offset:36864
	s_waitcnt vmcnt(0)
	ds_write_b128 v238, v[172:175] offset:36992
	s_waitcnt lgkmcnt(0)
	s_cbranch_scc1 .LBB0_1440
	v_mad_u32_u24 v0, v239, s30, 0
	v_lshl_add_u32 v235, v240, 3, v0
	v_sub_u32_e32 v0, v0, v201
	v_lshl_add_u32 v242, v241, 1, v0
	v_mov_b32_e32 v0, 0
	s_mov_b32 s8, 0
	v_mov_b32_e32 v1, v0
	v_mov_b32_e32 v2, v0
	v_mov_b32_e32 v3, v0
	v_mov_b32_e32 v4, v0
	v_mov_b32_e32 v5, v0
	v_mov_b32_e32 v6, v0
	v_mov_b32_e32 v7, v0
	v_mov_b32_e32 v8, v0
	v_mov_b32_e32 v9, v0
	v_mov_b32_e32 v10, v0
	v_mov_b32_e32 v11, v0
	v_mov_b32_e32 v12, v0
	v_mov_b32_e32 v13, v0
	v_mov_b32_e32 v14, v0
	v_mov_b32_e32 v15, v0
	v_mov_b32_e32 v16, v0
	v_mov_b32_e32 v17, v0
	v_mov_b32_e32 v18, v0
	v_mov_b32_e32 v19, v0
	v_mov_b32_e32 v20, v0
	v_mov_b32_e32 v21, v0
	v_mov_b32_e32 v22, v0
	v_mov_b32_e32 v23, v0
	v_mov_b32_e32 v24, v0
	v_mov_b32_e32 v25, v0
	v_mov_b32_e32 v26, v0
	v_mov_b32_e32 v27, v0
	v_mov_b32_e32 v28, v0
	v_mov_b32_e32 v29, v0
	v_mov_b32_e32 v30, v0
	v_mov_b32_e32 v31, v0
	v_mov_b32_e32 v32, v0
	v_mov_b32_e32 v33, v0
	v_mov_b32_e32 v34, v0
	v_mov_b32_e32 v35, v0
	v_mov_b32_e32 v36, v0
	v_mov_b32_e32 v37, v0
	v_mov_b32_e32 v38, v0
	v_mov_b32_e32 v39, v0
	v_mov_b32_e32 v40, v0
	v_mov_b32_e32 v41, v0
	v_mov_b32_e32 v42, v0
	v_mov_b32_e32 v43, v0
	v_mov_b32_e32 v44, v0
	v_mov_b32_e32 v45, v0
	v_mov_b32_e32 v46, v0
	v_mov_b32_e32 v47, v0
	v_mov_b32_e32 v48, v0
	v_mov_b32_e32 v49, v0
	v_mov_b32_e32 v50, v0
	v_mov_b32_e32 v51, v0
	v_mov_b32_e32 v52, v0
	v_mov_b32_e32 v53, v0
	v_mov_b32_e32 v54, v0
	v_mov_b32_e32 v55, v0
	v_mov_b32_e32 v56, v0
	v_mov_b32_e32 v57, v0
	v_mov_b32_e32 v58, v0
	v_mov_b32_e32 v59, v0
	v_mov_b32_e32 v60, v0
	v_mov_b32_e32 v61, v0
	v_mov_b32_e32 v62, v0
	v_mov_b32_e32 v63, v0
	v_mov_b32_e32 v206, v0
	v_mov_b32_e32 v207, v0
	s_barrier
